# scan phase rewritten by hand: all 34 chunk-state loads per thread in flight, wave-uniform scalar addressing
# speedup vs baseline: 1.0028x; 1.0028x over previous
.LBB0_282:
	s_nop 0
	v_readfirstlane_b32 s6, v7
	v_and_b32_e32 v0, 0x7ff, v7
	v_lshlrev_b32_e32 v0, 3, v0
	v_min_u32_e32 v5, 33, v220
	v_lshlrev_b32_e32 v5, 5, v5
	v_readlane_b32 s38, v251, 49
	v_readlane_b32 s39, v251, 50
	v_readlane_b32 s28, v251, 55
	v_readlane_b32 s29, v251, 56
	s_lshr_b32 s7, s6, 11
	s_and_b32 s3, s7, 1
	s_and_b32 s25, s7, 7
	s_lshr_b32 s7, s7, 3
	s_mul_i32 s7, s7, 0x110
	s_add_i32 s7, s7, s25
	s_lshl_b32 s25, s7, 2
	s_add_u32 s28, s28, s25
	s_addc_u32 s29, s29, 0
	global_load_dword v4, v5, s[28:29]
	s_lshl_b32 s25, s7, 14
	s_add_u32 s38, s38, s25
	s_addc_u32 s39, s39, 0
	s_cmp_eq_u32 s3, 1
	s_mov_b32 s36, 0x20000
	s_cselect_b32 s36, 0xfffe0000, s36
	s_cselect_b32 s37, -1, 0
	s_cselect_b32 s26, -1, 1
	s_lshl_b32 s6, s3, 17
	s_add_u32 s28, s38, s6
	s_addc_u32 s29, s39, 0
	global_load_dwordx2 v[62:63], v0, s[28:29]
	s_xor_b32 s6, s3, 1
	s_lshl_b32 s6, s6, 17
	s_add_u32 s28, s38, s6
	s_addc_u32 s29, s39, 0
	global_load_dwordx2 v[64:65], v0, s[28:29]
	s_cmp_eq_u32 s3, 1
	s_cselect_b32 s6, 33, 2
	s_lshl_b32 s6, s6, 17
	s_add_u32 s28, s38, s6
	s_addc_u32 s29, s39, 0
	global_load_dwordx2 v[66:67], v0, s[28:29]
	s_add_u32 s28, s28, s36
	s_addc_u32 s29, s29, s37
	global_load_dwordx2 v[68:69], v0, s[28:29]
	s_add_u32 s28, s28, s36
	s_addc_u32 s29, s29, s37
	global_load_dwordx2 v[70:71], v0, s[28:29]
	s_add_u32 s28, s28, s36
	s_addc_u32 s29, s29, s37
	global_load_dwordx2 v[72:73], v0, s[28:29]
	s_add_u32 s28, s28, s36
	s_addc_u32 s29, s29, s37
	global_load_dwordx2 v[74:75], v0, s[28:29]
	s_add_u32 s28, s28, s36
	s_addc_u32 s29, s29, s37
	global_load_dwordx2 v[76:77], v0, s[28:29]
	s_add_u32 s28, s28, s36
	s_addc_u32 s29, s29, s37
	global_load_dwordx2 v[78:79], v0, s[28:29]
	s_add_u32 s28, s28, s36
	s_addc_u32 s29, s29, s37
	global_load_dwordx2 v[80:81], v0, s[28:29]
	s_add_u32 s28, s28, s36
	s_addc_u32 s29, s29, s37
	global_load_dwordx2 v[82:83], v0, s[28:29]
	s_add_u32 s28, s28, s36
	s_addc_u32 s29, s29, s37
	global_load_dwordx2 v[84:85], v0, s[28:29]
	s_add_u32 s28, s28, s36
	s_addc_u32 s29, s29, s37
	global_load_dwordx2 v[86:87], v0, s[28:29]
	s_add_u32 s28, s28, s36
	s_addc_u32 s29, s29, s37
	global_load_dwordx2 v[88:89], v0, s[28:29]
	s_add_u32 s28, s28, s36
	s_addc_u32 s29, s29, s37
	global_load_dwordx2 v[90:91], v0, s[28:29]
	s_add_u32 s28, s28, s36
	s_addc_u32 s29, s29, s37
	global_load_dwordx2 v[92:93], v0, s[28:29]
	s_add_u32 s28, s28, s36
	s_addc_u32 s29, s29, s37
	global_load_dwordx2 v[94:95], v0, s[28:29]
	s_add_u32 s28, s28, s36
	s_addc_u32 s29, s29, s37
	global_load_dwordx2 v[96:97], v0, s[28:29]
	s_add_u32 s28, s28, s36
	s_addc_u32 s29, s29, s37
	global_load_dwordx2 v[98:99], v0, s[28:29]
	s_add_u32 s28, s28, s36
	s_addc_u32 s29, s29, s37
	global_load_dwordx2 v[104:105], v0, s[28:29]
	s_add_u32 s28, s28, s36
	s_addc_u32 s29, s29, s37
	global_load_dwordx2 v[106:107], v0, s[28:29]
	s_add_u32 s28, s28, s36
	s_addc_u32 s29, s29, s37
	global_load_dwordx2 v[108:109], v0, s[28:29]
	s_add_u32 s28, s28, s36
	s_addc_u32 s29, s29, s37
	global_load_dwordx2 v[110:111], v0, s[28:29]
	s_add_u32 s28, s28, s36
	s_addc_u32 s29, s29, s37
	global_load_dwordx2 v[112:113], v0, s[28:29]
	s_add_u32 s28, s28, s36
	s_addc_u32 s29, s29, s37
	global_load_dwordx2 v[120:121], v0, s[28:29]
	s_add_u32 s28, s28, s36
	s_addc_u32 s29, s29, s37
	global_load_dwordx2 v[122:123], v0, s[28:29]
	s_add_u32 s28, s28, s36
	s_addc_u32 s29, s29, s37
	global_load_dwordx2 v[124:125], v0, s[28:29]
	s_add_u32 s28, s28, s36
	s_addc_u32 s29, s29, s37
	global_load_dwordx2 v[126:127], v0, s[28:29]
	s_add_u32 s28, s28, s36
	s_addc_u32 s29, s29, s37
	global_load_dwordx2 v[130:131], v0, s[28:29]
	s_add_u32 s28, s28, s36
	s_addc_u32 s29, s29, s37
	global_load_dwordx2 v[132:133], v0, s[28:29]
	s_add_u32 s28, s28, s36
	s_addc_u32 s29, s29, s37
	global_load_dwordx2 v[134:135], v0, s[28:29]
	s_add_u32 s28, s28, s36
	s_addc_u32 s29, s29, s37
	global_load_dwordx2 v[138:139], v0, s[28:29]
	s_add_u32 s28, s28, s36
	s_addc_u32 s29, s29, s37
	global_load_dwordx2 v[140:141], v0, s[28:29]
	s_add_u32 s28, s28, s36
	s_addc_u32 s29, s29, s37
	global_load_dwordx2 v[142:143], v0, s[28:29]
	v_mov_b32_e32 v26, 0
	v_mov_b32_e32 v27, 0
	v_mov_b32_e32 v28, 0
	v_mov_b32_e32 v29, 0
	s_waitcnt vmcnt(34)
	s_mov_b32 s25, s3
	s_nop 0
	v_readlane_b32 s32, v4, s25
	s_lshl_b32 s6, s3, 17
	s_add_u32 s28, s38, s6
	s_addc_u32 s29, s39, 0
	s_xor_b32 s25, s3, 1
	v_cvt_pk_bf16_f32 v30, v26, v27
	v_cvt_pk_bf16_f32 v31, v28, v29
	v_readlane_b32 s34, v4, s25
	s_waitcnt vmcnt(33)
	global_store_dwordx2 v0, v[30:31], s[28:29]
	v_lshlrev_b32_e32 v40, 16, v62
	v_and_b32_e32 v41, 0xffff0000, v62
	v_lshlrev_b32_e32 v44, 16, v63
	v_and_b32_e32 v45, 0xffff0000, v63
	v_fma_f32 v26, v26, s32, v40
	v_fma_f32 v27, v27, s32, v41
	v_fma_f32 v28, v28, s32, v44
	v_fma_f32 v29, v29, s32, v45
	s_xor_b32 s6, s3, 1
	s_lshl_b32 s6, s6, 17
	s_add_u32 s28, s38, s6
	s_addc_u32 s29, s39, 0
	s_cmp_eq_u32 s3, 1
	s_cselect_b32 s25, 33, 2
	v_cvt_pk_bf16_f32 v32, v26, v27
	v_cvt_pk_bf16_f32 v33, v28, v29
	v_readlane_b32 s32, v4, s25
	s_waitcnt vmcnt(33)
	global_store_dwordx2 v0, v[32:33], s[28:29]
	v_lshlrev_b32_e32 v40, 16, v64
	v_and_b32_e32 v41, 0xffff0000, v64
	v_lshlrev_b32_e32 v44, 16, v65
	v_and_b32_e32 v45, 0xffff0000, v65
	v_fma_f32 v26, v26, s34, v40
	v_fma_f32 v27, v27, s34, v41
	v_fma_f32 v28, v28, s34, v44
	v_fma_f32 v29, v29, s34, v45
	s_cmp_eq_u32 s3, 1
	s_cselect_b32 s6, 33, 2
	s_lshl_b32 s6, s6, 17
	s_add_u32 s28, s38, s6
	s_addc_u32 s29, s39, 0
	s_add_i32 s25, s25, s26
	v_cvt_pk_bf16_f32 v30, v26, v27
	v_cvt_pk_bf16_f32 v31, v28, v29
	v_readlane_b32 s34, v4, s25
	s_waitcnt vmcnt(33)
	global_store_dwordx2 v0, v[30:31], s[28:29]
	v_lshlrev_b32_e32 v40, 16, v66
	v_and_b32_e32 v41, 0xffff0000, v66
	v_lshlrev_b32_e32 v44, 16, v67
	v_and_b32_e32 v45, 0xffff0000, v67
	v_fma_f32 v26, v26, s32, v40
	v_fma_f32 v27, v27, s32, v41
	v_fma_f32 v28, v28, s32, v44
	v_fma_f32 v29, v29, s32, v45
	s_add_u32 s28, s28, s36
	s_addc_u32 s29, s29, s37
	s_add_i32 s25, s25, s26
	v_cvt_pk_bf16_f32 v32, v26, v27
	v_cvt_pk_bf16_f32 v33, v28, v29
	v_readlane_b32 s32, v4, s25
	s_waitcnt vmcnt(33)
	global_store_dwordx2 v0, v[32:33], s[28:29]
	v_lshlrev_b32_e32 v40, 16, v68
	v_and_b32_e32 v41, 0xffff0000, v68
	v_lshlrev_b32_e32 v44, 16, v69
	v_and_b32_e32 v45, 0xffff0000, v69
	v_fma_f32 v26, v26, s34, v40
	v_fma_f32 v27, v27, s34, v41
	v_fma_f32 v28, v28, s34, v44
	v_fma_f32 v29, v29, s34, v45
	s_add_u32 s28, s28, s36
	s_addc_u32 s29, s29, s37
	s_add_i32 s25, s25, s26
	v_cvt_pk_bf16_f32 v30, v26, v27
	v_cvt_pk_bf16_f32 v31, v28, v29
	v_readlane_b32 s34, v4, s25
	s_waitcnt vmcnt(33)
	global_store_dwordx2 v0, v[30:31], s[28:29]
	v_lshlrev_b32_e32 v40, 16, v70
	v_and_b32_e32 v41, 0xffff0000, v70
	v_lshlrev_b32_e32 v44, 16, v71
	v_and_b32_e32 v45, 0xffff0000, v71
	v_fma_f32 v26, v26, s32, v40
	v_fma_f32 v27, v27, s32, v41
	v_fma_f32 v28, v28, s32, v44
	v_fma_f32 v29, v29, s32, v45
	s_add_u32 s28, s28, s36
	s_addc_u32 s29, s29, s37
	s_add_i32 s25, s25, s26
	v_cvt_pk_bf16_f32 v32, v26, v27
	v_cvt_pk_bf16_f32 v33, v28, v29
	v_readlane_b32 s32, v4, s25
	s_waitcnt vmcnt(33)
	global_store_dwordx2 v0, v[32:33], s[28:29]
	v_lshlrev_b32_e32 v40, 16, v72
	v_and_b32_e32 v41, 0xffff0000, v72
	v_lshlrev_b32_e32 v44, 16, v73
	v_and_b32_e32 v45, 0xffff0000, v73
	v_fma_f32 v26, v26, s34, v40
	v_fma_f32 v27, v27, s34, v41
	v_fma_f32 v28, v28, s34, v44
	v_fma_f32 v29, v29, s34, v45
	s_add_u32 s28, s28, s36
	s_addc_u32 s29, s29, s37
	s_add_i32 s25, s25, s26
	v_cvt_pk_bf16_f32 v30, v26, v27
	v_cvt_pk_bf16_f32 v31, v28, v29
	v_readlane_b32 s34, v4, s25
	s_waitcnt vmcnt(33)
	global_store_dwordx2 v0, v[30:31], s[28:29]
	v_lshlrev_b32_e32 v40, 16, v74
	v_and_b32_e32 v41, 0xffff0000, v74
	v_lshlrev_b32_e32 v44, 16, v75
	v_and_b32_e32 v45, 0xffff0000, v75
	v_fma_f32 v26, v26, s32, v40
	v_fma_f32 v27, v27, s32, v41
	v_fma_f32 v28, v28, s32, v44
	v_fma_f32 v29, v29, s32, v45
	s_add_u32 s28, s28, s36
	s_addc_u32 s29, s29, s37
	s_add_i32 s25, s25, s26
	v_cvt_pk_bf16_f32 v32, v26, v27
	v_cvt_pk_bf16_f32 v33, v28, v29
	v_readlane_b32 s32, v4, s25
	s_waitcnt vmcnt(33)
	global_store_dwordx2 v0, v[32:33], s[28:29]
	v_lshlrev_b32_e32 v40, 16, v76
	v_and_b32_e32 v41, 0xffff0000, v76
	v_lshlrev_b32_e32 v44, 16, v77
	v_and_b32_e32 v45, 0xffff0000, v77
	v_fma_f32 v26, v26, s34, v40
	v_fma_f32 v27, v27, s34, v41
	v_fma_f32 v28, v28, s34, v44
	v_fma_f32 v29, v29, s34, v45
	s_add_u32 s28, s28, s36
	s_addc_u32 s29, s29, s37
	s_add_i32 s25, s25, s26
	v_cvt_pk_bf16_f32 v30, v26, v27
	v_cvt_pk_bf16_f32 v31, v28, v29
	v_readlane_b32 s34, v4, s25
	s_waitcnt vmcnt(33)
	global_store_dwordx2 v0, v[30:31], s[28:29]
	v_lshlrev_b32_e32 v40, 16, v78
	v_and_b32_e32 v41, 0xffff0000, v78
	v_lshlrev_b32_e32 v44, 16, v79
	v_and_b32_e32 v45, 0xffff0000, v79
	v_fma_f32 v26, v26, s32, v40
	v_fma_f32 v27, v27, s32, v41
	v_fma_f32 v28, v28, s32, v44
	v_fma_f32 v29, v29, s32, v45
	s_add_u32 s28, s28, s36
	s_addc_u32 s29, s29, s37
	s_add_i32 s25, s25, s26
	v_cvt_pk_bf16_f32 v32, v26, v27
	v_cvt_pk_bf16_f32 v33, v28, v29
	v_readlane_b32 s32, v4, s25
	s_waitcnt vmcnt(33)
	global_store_dwordx2 v0, v[32:33], s[28:29]
	v_lshlrev_b32_e32 v40, 16, v80
	v_and_b32_e32 v41, 0xffff0000, v80
	v_lshlrev_b32_e32 v44, 16, v81
	v_and_b32_e32 v45, 0xffff0000, v81
	v_fma_f32 v26, v26, s34, v40
	v_fma_f32 v27, v27, s34, v41
	v_fma_f32 v28, v28, s34, v44
	v_fma_f32 v29, v29, s34, v45
	s_add_u32 s28, s28, s36
	s_addc_u32 s29, s29, s37
	s_add_i32 s25, s25, s26
	v_cvt_pk_bf16_f32 v30, v26, v27
	v_cvt_pk_bf16_f32 v31, v28, v29
	v_readlane_b32 s34, v4, s25
	s_waitcnt vmcnt(33)
	global_store_dwordx2 v0, v[30:31], s[28:29]
	v_lshlrev_b32_e32 v40, 16, v82
	v_and_b32_e32 v41, 0xffff0000, v82
	v_lshlrev_b32_e32 v44, 16, v83
	v_and_b32_e32 v45, 0xffff0000, v83
	v_fma_f32 v26, v26, s32, v40
	v_fma_f32 v27, v27, s32, v41
	v_fma_f32 v28, v28, s32, v44
	v_fma_f32 v29, v29, s32, v45
	s_add_u32 s28, s28, s36
	s_addc_u32 s29, s29, s37
	s_add_i32 s25, s25, s26
	v_cvt_pk_bf16_f32 v32, v26, v27
	v_cvt_pk_bf16_f32 v33, v28, v29
	v_readlane_b32 s32, v4, s25
	s_waitcnt vmcnt(33)
	global_store_dwordx2 v0, v[32:33], s[28:29]
	v_lshlrev_b32_e32 v40, 16, v84
	v_and_b32_e32 v41, 0xffff0000, v84
	v_lshlrev_b32_e32 v44, 16, v85
	v_and_b32_e32 v45, 0xffff0000, v85
	v_fma_f32 v26, v26, s34, v40
	v_fma_f32 v27, v27, s34, v41
	v_fma_f32 v28, v28, s34, v44
	v_fma_f32 v29, v29, s34, v45
	s_add_u32 s28, s28, s36
	s_addc_u32 s29, s29, s37
	s_add_i32 s25, s25, s26
	v_cvt_pk_bf16_f32 v30, v26, v27
	v_cvt_pk_bf16_f32 v31, v28, v29
	v_readlane_b32 s34, v4, s25
	s_waitcnt vmcnt(33)
	global_store_dwordx2 v0, v[30:31], s[28:29]
	v_lshlrev_b32_e32 v40, 16, v86
	v_and_b32_e32 v41, 0xffff0000, v86
	v_lshlrev_b32_e32 v44, 16, v87
	v_and_b32_e32 v45, 0xffff0000, v87
	v_fma_f32 v26, v26, s32, v40
	v_fma_f32 v27, v27, s32, v41
	v_fma_f32 v28, v28, s32, v44
	v_fma_f32 v29, v29, s32, v45
	s_add_u32 s28, s28, s36
	s_addc_u32 s29, s29, s37
	s_add_i32 s25, s25, s26
	v_cvt_pk_bf16_f32 v32, v26, v27
	v_cvt_pk_bf16_f32 v33, v28, v29
	v_readlane_b32 s32, v4, s25
	s_waitcnt vmcnt(33)
	global_store_dwordx2 v0, v[32:33], s[28:29]
	v_lshlrev_b32_e32 v40, 16, v88
	v_and_b32_e32 v41, 0xffff0000, v88
	v_lshlrev_b32_e32 v44, 16, v89
	v_and_b32_e32 v45, 0xffff0000, v89
	v_fma_f32 v26, v26, s34, v40
	v_fma_f32 v27, v27, s34, v41
	v_fma_f32 v28, v28, s34, v44
	v_fma_f32 v29, v29, s34, v45
	s_add_u32 s28, s28, s36
	s_addc_u32 s29, s29, s37
	s_add_i32 s25, s25, s26
	v_cvt_pk_bf16_f32 v30, v26, v27
	v_cvt_pk_bf16_f32 v31, v28, v29
	v_readlane_b32 s34, v4, s25
	s_waitcnt vmcnt(33)
	global_store_dwordx2 v0, v[30:31], s[28:29]
	v_lshlrev_b32_e32 v40, 16, v90
	v_and_b32_e32 v41, 0xffff0000, v90
	v_lshlrev_b32_e32 v44, 16, v91
	v_and_b32_e32 v45, 0xffff0000, v91
	v_fma_f32 v26, v26, s32, v40
	v_fma_f32 v27, v27, s32, v41
	v_fma_f32 v28, v28, s32, v44
	v_fma_f32 v29, v29, s32, v45
	s_add_u32 s28, s28, s36
	s_addc_u32 s29, s29, s37
	s_add_i32 s25, s25, s26
	v_cvt_pk_bf16_f32 v32, v26, v27
	v_cvt_pk_bf16_f32 v33, v28, v29
	v_readlane_b32 s32, v4, s25
	s_waitcnt vmcnt(33)
	global_store_dwordx2 v0, v[32:33], s[28:29]
	v_lshlrev_b32_e32 v40, 16, v92
	v_and_b32_e32 v41, 0xffff0000, v92
	v_lshlrev_b32_e32 v44, 16, v93
	v_and_b32_e32 v45, 0xffff0000, v93
	v_fma_f32 v26, v26, s34, v40
	v_fma_f32 v27, v27, s34, v41
	v_fma_f32 v28, v28, s34, v44
	v_fma_f32 v29, v29, s34, v45
	s_add_u32 s28, s28, s36
	s_addc_u32 s29, s29, s37
	s_add_i32 s25, s25, s26
	v_cvt_pk_bf16_f32 v30, v26, v27
	v_cvt_pk_bf16_f32 v31, v28, v29
	v_readlane_b32 s34, v4, s25
	s_waitcnt vmcnt(33)
	global_store_dwordx2 v0, v[30:31], s[28:29]
	v_lshlrev_b32_e32 v40, 16, v94
	v_and_b32_e32 v41, 0xffff0000, v94
	v_lshlrev_b32_e32 v44, 16, v95
	v_and_b32_e32 v45, 0xffff0000, v95
	v_fma_f32 v26, v26, s32, v40
	v_fma_f32 v27, v27, s32, v41
	v_fma_f32 v28, v28, s32, v44
	v_fma_f32 v29, v29, s32, v45
	s_add_u32 s28, s28, s36
	s_addc_u32 s29, s29, s37
	s_add_i32 s25, s25, s26
	v_cvt_pk_bf16_f32 v32, v26, v27
	v_cvt_pk_bf16_f32 v33, v28, v29
	v_readlane_b32 s32, v4, s25
	s_waitcnt vmcnt(33)
	global_store_dwordx2 v0, v[32:33], s[28:29]
	v_lshlrev_b32_e32 v40, 16, v96
	v_and_b32_e32 v41, 0xffff0000, v96
	v_lshlrev_b32_e32 v44, 16, v97
	v_and_b32_e32 v45, 0xffff0000, v97
	v_fma_f32 v26, v26, s34, v40
	v_fma_f32 v27, v27, s34, v41
	v_fma_f32 v28, v28, s34, v44
	v_fma_f32 v29, v29, s34, v45
	s_add_u32 s28, s28, s36
	s_addc_u32 s29, s29, s37
	s_add_i32 s25, s25, s26
	v_cvt_pk_bf16_f32 v30, v26, v27
	v_cvt_pk_bf16_f32 v31, v28, v29
	v_readlane_b32 s34, v4, s25
	s_waitcnt vmcnt(33)
	global_store_dwordx2 v0, v[30:31], s[28:29]
	v_lshlrev_b32_e32 v40, 16, v98
	v_and_b32_e32 v41, 0xffff0000, v98
	v_lshlrev_b32_e32 v44, 16, v99
	v_and_b32_e32 v45, 0xffff0000, v99
	v_fma_f32 v26, v26, s32, v40
	v_fma_f32 v27, v27, s32, v41
	v_fma_f32 v28, v28, s32, v44
	v_fma_f32 v29, v29, s32, v45
	s_add_u32 s28, s28, s36
	s_addc_u32 s29, s29, s37
	s_add_i32 s25, s25, s26
	v_cvt_pk_bf16_f32 v32, v26, v27
	v_cvt_pk_bf16_f32 v33, v28, v29
	v_readlane_b32 s32, v4, s25
	s_waitcnt vmcnt(33)
	global_store_dwordx2 v0, v[32:33], s[28:29]
	v_lshlrev_b32_e32 v40, 16, v104
	v_and_b32_e32 v41, 0xffff0000, v104
	v_lshlrev_b32_e32 v44, 16, v105
	v_and_b32_e32 v45, 0xffff0000, v105
	v_fma_f32 v26, v26, s34, v40
	v_fma_f32 v27, v27, s34, v41
	v_fma_f32 v28, v28, s34, v44
	v_fma_f32 v29, v29, s34, v45
	s_add_u32 s28, s28, s36
	s_addc_u32 s29, s29, s37
	s_add_i32 s25, s25, s26
	v_cvt_pk_bf16_f32 v30, v26, v27
	v_cvt_pk_bf16_f32 v31, v28, v29
	v_readlane_b32 s34, v4, s25
	s_waitcnt vmcnt(33)
	global_store_dwordx2 v0, v[30:31], s[28:29]
	v_lshlrev_b32_e32 v40, 16, v106
	v_and_b32_e32 v41, 0xffff0000, v106
	v_lshlrev_b32_e32 v44, 16, v107
	v_and_b32_e32 v45, 0xffff0000, v107
	v_fma_f32 v26, v26, s32, v40
	v_fma_f32 v27, v27, s32, v41
	v_fma_f32 v28, v28, s32, v44
	v_fma_f32 v29, v29, s32, v45
	s_add_u32 s28, s28, s36
	s_addc_u32 s29, s29, s37
	s_add_i32 s25, s25, s26
	v_cvt_pk_bf16_f32 v32, v26, v27
	v_cvt_pk_bf16_f32 v33, v28, v29
	v_readlane_b32 s32, v4, s25
	s_waitcnt vmcnt(33)
	global_store_dwordx2 v0, v[32:33], s[28:29]
	v_lshlrev_b32_e32 v40, 16, v108
	v_and_b32_e32 v41, 0xffff0000, v108
	v_lshlrev_b32_e32 v44, 16, v109
	v_and_b32_e32 v45, 0xffff0000, v109
	v_fma_f32 v26, v26, s34, v40
	v_fma_f32 v27, v27, s34, v41
	v_fma_f32 v28, v28, s34, v44
	v_fma_f32 v29, v29, s34, v45
	s_add_u32 s28, s28, s36
	s_addc_u32 s29, s29, s37
	s_add_i32 s25, s25, s26
	v_cvt_pk_bf16_f32 v30, v26, v27
	v_cvt_pk_bf16_f32 v31, v28, v29
	v_readlane_b32 s34, v4, s25
	s_waitcnt vmcnt(33)
	global_store_dwordx2 v0, v[30:31], s[28:29]
	v_lshlrev_b32_e32 v40, 16, v110
	v_and_b32_e32 v41, 0xffff0000, v110
	v_lshlrev_b32_e32 v44, 16, v111
	v_and_b32_e32 v45, 0xffff0000, v111
	v_fma_f32 v26, v26, s32, v40
	v_fma_f32 v27, v27, s32, v41
	v_fma_f32 v28, v28, s32, v44
	v_fma_f32 v29, v29, s32, v45
	s_add_u32 s28, s28, s36
	s_addc_u32 s29, s29, s37
	s_add_i32 s25, s25, s26
	v_cvt_pk_bf16_f32 v32, v26, v27
	v_cvt_pk_bf16_f32 v33, v28, v29
	v_readlane_b32 s32, v4, s25
	s_waitcnt vmcnt(33)
	global_store_dwordx2 v0, v[32:33], s[28:29]
	v_lshlrev_b32_e32 v40, 16, v112
	v_and_b32_e32 v41, 0xffff0000, v112
	v_lshlrev_b32_e32 v44, 16, v113
	v_and_b32_e32 v45, 0xffff0000, v113
	v_fma_f32 v26, v26, s34, v40
	v_fma_f32 v27, v27, s34, v41
	v_fma_f32 v28, v28, s34, v44
	v_fma_f32 v29, v29, s34, v45
	s_add_u32 s28, s28, s36
	s_addc_u32 s29, s29, s37
	s_add_i32 s25, s25, s26
	v_cvt_pk_bf16_f32 v30, v26, v27
	v_cvt_pk_bf16_f32 v31, v28, v29
	v_readlane_b32 s34, v4, s25
	s_waitcnt vmcnt(33)
	global_store_dwordx2 v0, v[30:31], s[28:29]
	v_lshlrev_b32_e32 v40, 16, v120
	v_and_b32_e32 v41, 0xffff0000, v120
	v_lshlrev_b32_e32 v44, 16, v121
	v_and_b32_e32 v45, 0xffff0000, v121
	v_fma_f32 v26, v26, s32, v40
	v_fma_f32 v27, v27, s32, v41
	v_fma_f32 v28, v28, s32, v44
	v_fma_f32 v29, v29, s32, v45
	s_add_u32 s28, s28, s36
	s_addc_u32 s29, s29, s37
	s_add_i32 s25, s25, s26
	v_cvt_pk_bf16_f32 v32, v26, v27
	v_cvt_pk_bf16_f32 v33, v28, v29
	v_readlane_b32 s32, v4, s25
	s_waitcnt vmcnt(33)
	global_store_dwordx2 v0, v[32:33], s[28:29]
	v_lshlrev_b32_e32 v40, 16, v122
	v_and_b32_e32 v41, 0xffff0000, v122
	v_lshlrev_b32_e32 v44, 16, v123
	v_and_b32_e32 v45, 0xffff0000, v123
	v_fma_f32 v26, v26, s34, v40
	v_fma_f32 v27, v27, s34, v41
	v_fma_f32 v28, v28, s34, v44
	v_fma_f32 v29, v29, s34, v45
	s_add_u32 s28, s28, s36
	s_addc_u32 s29, s29, s37
	s_add_i32 s25, s25, s26
	v_cvt_pk_bf16_f32 v30, v26, v27
	v_cvt_pk_bf16_f32 v31, v28, v29
	v_readlane_b32 s34, v4, s25
	s_waitcnt vmcnt(33)
	global_store_dwordx2 v0, v[30:31], s[28:29]
	v_lshlrev_b32_e32 v40, 16, v124
	v_and_b32_e32 v41, 0xffff0000, v124
	v_lshlrev_b32_e32 v44, 16, v125
	v_and_b32_e32 v45, 0xffff0000, v125
	v_fma_f32 v26, v26, s32, v40
	v_fma_f32 v27, v27, s32, v41
	v_fma_f32 v28, v28, s32, v44
	v_fma_f32 v29, v29, s32, v45
	s_add_u32 s28, s28, s36
	s_addc_u32 s29, s29, s37
	s_add_i32 s25, s25, s26
	v_cvt_pk_bf16_f32 v32, v26, v27
	v_cvt_pk_bf16_f32 v33, v28, v29
	v_readlane_b32 s32, v4, s25
	s_waitcnt vmcnt(33)
	global_store_dwordx2 v0, v[32:33], s[28:29]
	v_lshlrev_b32_e32 v40, 16, v126
	v_and_b32_e32 v41, 0xffff0000, v126
	v_lshlrev_b32_e32 v44, 16, v127
	v_and_b32_e32 v45, 0xffff0000, v127
	v_fma_f32 v26, v26, s34, v40
	v_fma_f32 v27, v27, s34, v41
	v_fma_f32 v28, v28, s34, v44
	v_fma_f32 v29, v29, s34, v45
	s_add_u32 s28, s28, s36
	s_addc_u32 s29, s29, s37
	s_add_i32 s25, s25, s26
	v_cvt_pk_bf16_f32 v30, v26, v27
	v_cvt_pk_bf16_f32 v31, v28, v29
	v_readlane_b32 s34, v4, s25
	s_waitcnt vmcnt(33)
	global_store_dwordx2 v0, v[30:31], s[28:29]
	v_lshlrev_b32_e32 v40, 16, v130
	v_and_b32_e32 v41, 0xffff0000, v130
	v_lshlrev_b32_e32 v44, 16, v131
	v_and_b32_e32 v45, 0xffff0000, v131
	v_fma_f32 v26, v26, s32, v40
	v_fma_f32 v27, v27, s32, v41
	v_fma_f32 v28, v28, s32, v44
	v_fma_f32 v29, v29, s32, v45
	s_add_u32 s28, s28, s36
	s_addc_u32 s29, s29, s37
	s_add_i32 s25, s25, s26
	v_cvt_pk_bf16_f32 v32, v26, v27
	v_cvt_pk_bf16_f32 v33, v28, v29
	v_readlane_b32 s32, v4, s25
	s_waitcnt vmcnt(33)
	global_store_dwordx2 v0, v[32:33], s[28:29]
	v_lshlrev_b32_e32 v40, 16, v132
	v_and_b32_e32 v41, 0xffff0000, v132
	v_lshlrev_b32_e32 v44, 16, v133
	v_and_b32_e32 v45, 0xffff0000, v133
	v_fma_f32 v26, v26, s34, v40
	v_fma_f32 v27, v27, s34, v41
	v_fma_f32 v28, v28, s34, v44
	v_fma_f32 v29, v29, s34, v45
	s_add_u32 s28, s28, s36
	s_addc_u32 s29, s29, s37
	s_add_i32 s25, s25, s26
	v_cvt_pk_bf16_f32 v30, v26, v27
	v_cvt_pk_bf16_f32 v31, v28, v29
	v_readlane_b32 s34, v4, s25
	s_waitcnt vmcnt(33)
	global_store_dwordx2 v0, v[30:31], s[28:29]
	v_lshlrev_b32_e32 v40, 16, v134
	v_and_b32_e32 v41, 0xffff0000, v134
	v_lshlrev_b32_e32 v44, 16, v135
	v_and_b32_e32 v45, 0xffff0000, v135
	v_fma_f32 v26, v26, s32, v40
	v_fma_f32 v27, v27, s32, v41
	v_fma_f32 v28, v28, s32, v44
	v_fma_f32 v29, v29, s32, v45
	s_add_u32 s28, s28, s36
	s_addc_u32 s29, s29, s37
	s_add_i32 s25, s25, s26
	v_cvt_pk_bf16_f32 v32, v26, v27
	v_cvt_pk_bf16_f32 v33, v28, v29
	v_readlane_b32 s32, v4, s25
	s_waitcnt vmcnt(33)
	global_store_dwordx2 v0, v[32:33], s[28:29]
	v_lshlrev_b32_e32 v40, 16, v138
	v_and_b32_e32 v41, 0xffff0000, v138
	v_lshlrev_b32_e32 v44, 16, v139
	v_and_b32_e32 v45, 0xffff0000, v139
	v_fma_f32 v26, v26, s34, v40
	v_fma_f32 v27, v27, s34, v41
	v_fma_f32 v28, v28, s34, v44
	v_fma_f32 v29, v29, s34, v45
	s_add_u32 s28, s28, s36
	s_addc_u32 s29, s29, s37
	s_add_i32 s25, s25, s26
	v_cvt_pk_bf16_f32 v30, v26, v27
	v_cvt_pk_bf16_f32 v31, v28, v29
	v_readlane_b32 s34, v4, s25
	s_waitcnt vmcnt(33)
	global_store_dwordx2 v0, v[30:31], s[28:29]
	v_lshlrev_b32_e32 v40, 16, v140
	v_and_b32_e32 v41, 0xffff0000, v140
	v_lshlrev_b32_e32 v44, 16, v141
	v_and_b32_e32 v45, 0xffff0000, v141
	v_fma_f32 v26, v26, s32, v40
	v_fma_f32 v27, v27, s32, v41
	v_fma_f32 v28, v28, s32, v44
	v_fma_f32 v29, v29, s32, v45
	s_add_u32 s28, s28, s36
	s_addc_u32 s29, s29, s37
	v_cvt_pk_bf16_f32 v32, v26, v27
	v_cvt_pk_bf16_f32 v33, v28, v29
	s_waitcnt vmcnt(33)
	global_store_dwordx2 v0, v[32:33], s[28:29]
	v_lshlrev_b32_e32 v40, 16, v142
	v_and_b32_e32 v41, 0xffff0000, v142
	v_lshlrev_b32_e32 v44, 16, v143
	v_and_b32_e32 v45, 0xffff0000, v143
	v_fma_f32 v26, v26, s34, v40
	v_fma_f32 v27, v27, s34, v41
	v_fma_f32 v28, v28, s34, v44
	v_fma_f32 v29, v29, s34, v45
	s_branch .LBB0_281
